# local barrier a split: arrive right after the in-projection loop (before V^T / weight conversion), wait before M1
# speedup vs baseline: 1.0244x; 1.0045x over previous
.LBB0_198:
	v_readlane_b32 s74, v255, 62
	s_nop 3
	s_cmp_eq_u32 s74, 0
	s_cbranch_scc1 .Learly_a_done
	s_mov_b64 s[76:77], exec
	v_readlane_b32 s78, v252, 11
	v_readlane_b32 s79, v252, 12
	s_nop 3
	s_and_b64 s[78:79], s[76:77], s[78:79]
	s_mov_b64 exec, s[78:79]
	s_cbranch_execz .Learly_a_rest
	v_readlane_b32 s80, v253, 26
	v_readlane_b32 s81, v253, 27
	s_nop 3
	s_add_u32 s80, s80, 0x2300
	s_addc_u32 s81, s81, 0
	v_mov_b32_e32 v1, 1
	s_nop 1
	global_atomic_add v3, v1, s[80:81]
.Learly_a_rest:
	s_mov_b64 exec, s[76:77]
.Learly_a_done:
	v_readlane_b32 s4, v254, 40
	v_mov_b32_e32 v18, v0
	v_readlane_b32 s5, v254, 41
	s_andn2_b64 vcc, exec, s[4:5]
	v_readfirstlane_b32 s14, v18
	s_cbranch_vccnz .LBB0_220
	v_readlane_b32 s4, v254, 45
	v_readlane_b32 s5, v254, 46
	s_mov_b32 s66, s26
	s_andn2_b64 vcc, exec, s[4:5]
	v_readlane_b32 s4, v254, 48
	s_cbranch_vccnz .LBB0_201
	v_readlane_b32 s4, v254, 47

.LBB0_256:
	v_readlane_b32 s0, v255, 13
	v_readlane_b32 s4, v252, 7
	s_add_i32 s10, s0, 2
	v_readlane_b32 s7, v252, 10
	s_cmp_ge_i32 s10, s7
	s_barrier
	v_readlane_b32 s5, v252, 8
	v_readlane_b32 s6, v252, 9
	s_cbranch_scc1 .LBB0_310
	v_readlane_b32 s74, v255, 62
	s_nop 3
	s_cmp_eq_u32 s74, 0
	s_cbranch_scc1 .Lglob_a
	s_waitcnt vmcnt(0) lgkmcnt(0)
	s_barrier
	s_mov_b64 s[76:77], exec
	v_readlane_b32 s78, v252, 11
	v_readlane_b32 s79, v252, 12
	s_nop 3
	s_and_b64 s[78:79], s[76:77], s[78:79]
	s_mov_b64 exec, s[78:79]
	s_cbranch_execz .Lloc_done_a
	v_readlane_b32 s80, v253, 26
	v_readlane_b32 s81, v253, 27
	v_readlane_b32 s82, v255, 13
	s_nop 3
	s_add_u32 s80, s80, 0x2300
	s_addc_u32 s81, s81, 0
	s_cmp_lg_u32 s82, 0
	s_cselect_b32 s82, 0x40, 0
	s_add_i32 s82, s82, 32
	s_mov_b32 s84, 0
.Lloc_spin_a:
	global_load_dword v2, v3, s[80:81] sc1
	s_waitcnt vmcnt(0)
	v_readfirstlane_b32 s83, v2
	s_nop 3
	s_cmp_ge_u32 s83, s82
	s_cbranch_scc1 .Lloc_rel_a
	s_add_i32 s84, s84, 1
	s_cmp_gt_u32 s84, 0x40000
	s_cbranch_scc1 .Lloc_rel_a
	s_sleep 1
	s_branch .Lloc_spin_a
